# grid barrier: the per-CU L1 invalidate (buffer_inv sc1) is issued right behind the first poll / after the L2 writeback instead of after the release is observed (no vector L1 fills can happen in betwee
# speedup vs baseline: 1.0325x; 1.0105x over previous
.LBB0_2113:
	s_or_b64 exec, exec, s[2:3]
	v_cvt_f32_u32_e32 v4, v2
	s_waitcnt vmcnt(0)
	v_readfirstlane_b32 s2, v3
	v_sub_u32_e32 v3, 0, v2
	v_rcp_iflag_f32_e32 v4, v4
	v_add_u32_e32 v5, s2, v1
	v_mul_f32_e32 v4, 0x4f7ffffe, v4
	v_cvt_u32_f32_e32 v4, v4
	v_mul_lo_u32 v1, v3, v4
	v_mul_hi_u32 v1, v4, v1
	v_add_u32_e32 v1, v4, v1
	v_mul_hi_u32 v1, v5, v1
	v_mul_lo_u32 v3, v1, v2
	v_sub_u32_e32 v3, v5, v3
	v_add_u32_e32 v4, 1, v1
	v_cmp_ge_u32_e32 vcc, v3, v2
	s_nop 1
	v_cndmask_b32_e32 v1, v1, v4, vcc
	v_sub_u32_e32 v4, v3, v2
	v_cndmask_b32_e32 v3, v3, v4, vcc
	v_add_u32_e32 v4, 1, v1
	v_cmp_ge_u32_e32 vcc, v3, v2
	v_add_u32_e32 v3, 1, v5
	s_nop 0
	v_cndmask_b32_e32 v1, v1, v4, vcc
	v_mul_lo_u32 v4, v2, v1
	v_add_u32_e32 v2, v4, v2
	v_cmp_ne_u32_e32 vcc, v3, v2
	s_and_saveexec_b64 s[2:3], vcc
	s_xor_b64 s[2:3], exec, s[2:3]
	s_cbranch_execz .LBB0_2127
	v_readlane_b32 s4, v254, 62
	v_readlane_b32 s5, v254, 63
	s_waitcnt lgkmcnt(0)
	s_nop 3
	global_load_dword v0, v20, s[4:5] sc1
	buffer_inv sc1
	s_waitcnt vmcnt(1)
	v_cmp_eq_u32_e32 vcc, v0, v1
	s_and_saveexec_b64 s[4:5], vcc
	s_cbranch_execz .LBB0_2126
	s_mov_b32 s16, 1
	s_mov_b64 s[6:7], 0
	s_branch .LBB0_2117

.LBB0_2126:
	s_or_b64 exec, exec, s[4:5]
	s_waitcnt vmcnt(0)
	s_waitcnt vmcnt(0)
.LBB0_2127:
	s_andn2_saveexec_b64 s[2:3], s[2:3]
	s_cbranch_execz .LBB0_2147
	s_mov_b64 s[2:3], exec
	buffer_wbl2 sc1
	s_waitcnt lgkmcnt(0)
	s_waitcnt vmcnt(0)
	buffer_inv sc1
	v_mbcnt_lo_u32_b32 v1, s2, 0
	v_mbcnt_hi_u32_b32 v1, s3, v1
	v_cmp_eq_u32_e32 vcc, 0, v1
	s_and_saveexec_b64 s[4:5], vcc
	s_cbranch_execz .LBB0_2130
	s_bcnt1_i32_b64 s2, s[2:3]
	v_mov_b32_e32 v2, s2
	v_readlane_b32 s2, v255, 0
	v_readlane_b32 s3, v255, 1
	s_nop 4
	global_atomic_add v2, v20, v2, s[2:3] sc0

.LBB0_2144:
	s_or_b64 exec, exec, s[2:3]
	s_mov_b64 s[2:3], exec
	v_mbcnt_lo_u32_b32 v0, s2, 0
	v_mbcnt_hi_u32_b32 v0, s3, v0
	v_cmp_eq_u32_e32 vcc, 0, v0
	s_waitcnt vmcnt(0)
	s_and_saveexec_b64 s[4:5], vcc
	s_cbranch_execz .LBB0_2146
	s_bcnt1_i32_b64 s2, s[2:3]
	v_mov_b32_e32 v0, s2
	v_readlane_b32 s2, v254, 62
	v_readlane_b32 s3, v254, 63
	s_nop 4
	global_atomic_add v20, v0, s[2:3]
